# prologue converter f32 weight loads with nt hint (read-once stream), on top of packed norm + hand-written converter
# baseline (speedup 1.0000x reference)
; __device__ __forceinline__ void tr_load(const float* src, int N, f32x4 (&v)[16], int lane) {
;     const int r4 = lane >> 4, c4 = (lane & 15) * 4;
; #pragma unroll
;     for (int i = 0; i < 16; ++i) v[i] = *(const f32x4*)(src + (size_t)(4 * i + r4) * N + c4);
; __device__ __forceinline__ void convert_segments(const Args& args, unsigned char* ws, LAS unsigned char* lds, int seg_lo, int seg_hi, int part_lo, int part_hi, int nparts, int wid, int nw, int wave, int lane) {
;     ...
;     for (int sI = seg_lo; sI < seg_hi; ++sI) {
;         const Seg sg = seg_at(sI);
;         const int nblk = sg.ncols / 64, nit = (sg.K / 64) * nblk;
;         const float* W = args.in[sg.in_idx] + (size_t)sg.src_l * sg.K * sg.N;
;         bf16* WT = (bf16*)(ws + WS_W + (size_t)sg.layer * LAYER_W + (size_t)sg.wsub_mib * MiB);
;         const int it_lo = (int)((long)nit * part_lo / nparts), it_hi = (int)((long)nit * part_hi / nparts);
;         int it = it_lo + wid;
;         f32x4 v[16];
;         if (it < it_hi) { const int kb = it / nblk, nb = it - kb * nblk; tr_load(W + (size_t)(64 * kb) * sg.N + sg.scol + 64 * nb, sg.N, v, lane); }
cvp_seg:
	s_cmp_ge_u32 s70, s61
	s_cbranch_scc1 cvp_done
	s_mul_i32 s4, s70, 40
	s_getpc_b64 s[6:7]
	s_add_u32 s6, s6, __const._Z6seg_ati.segs@rel32@lo+4
	s_addc_u32 s7, s7, __const._Z6seg_ati.segs@rel32@hi+12
	s_add_u32 s6, s6, s4
	s_addc_u32 s7, s7, 0
	s_load_dwordx8 s[8:15], s[6:7], 0x0
	s_load_dwordx2 s[18:19], s[6:7], 0x20
	s_waitcnt lgkmcnt(0)
	s_lshr_b32 s20, s13, 6
	s_lshr_b32 s21, s11, 6
	s_mul_i32 s22, s20, s21
	s_lshl_b32 s4, s8, 3
	s_load_dwordx2 s[24:25], s[0:1], s4
	s_mul_i32 s5, s11, s10
	s_mul_i32 s5, s5, s9
	s_lshl_b32 s5, s5, 2
	s_lshl_b32 s6, s12, 2
	s_add_u32 s5, s5, s6
	s_waitcnt lgkmcnt(0)
	s_add_u32 s24, s24, s5
	s_addc_u32 s25, s25, 0
	s_mul_i32 s5, s14, 0x1a400000
	s_lshl_b32 s6, s15, 20
	s_add_u32 s5, s5, s6
	s_add_u32 s5, s5, 0x2d400000
	s_add_u32 s26, s68, s5
	s_addc_u32 s27, s69, 0
	s_mov_b32 s41, 0
	s_mov_b32 s42, s22
	s_add_i32 s43, s62, s67
	s_cmp_ge_u32 s43, s63
	s_cselect_b32 s4, s63, 0
	s_sub_i32 s43, s43, s4
	s_sub_i32 s4, s42, s41
	s_sub_i32 s67, s67, s4
	s_and_b32 s67, s67, s71
	s_add_i32 s43, s43, s41
	s_cmp_ge_i32 s43, s42
	s_cbranch_scc1 cvp_next
	v_cvt_f32_u32_e32 v170, s63
	v_cvt_f32_u32_e32 v171, s20
	v_rcp_f32_e32 v171, v171
	s_nop 1
	v_mul_f32_e32 v170, v170, v171
	v_cvt_u32_f32_e32 v170, v170
	s_nop 1
	v_readfirstlane_b32 s44, v170
	s_mul_i32 s72, s44, s20
	s_sub_i32 s45, s63, s72
	s_cmp_lt_i32 s45, 0
	s_cselect_b32 s72, s20, 0
	s_cselect_b32 s73, 1, 0
	s_add_i32 s45, s45, s72
	s_sub_i32 s44, s44, s73
	s_cmp_ge_i32 s45, s20
	s_cselect_b32 s72, s20, 0
	s_cselect_b32 s73, 1, 0
	s_sub_i32 s45, s45, s72
	s_add_i32 s44, s44, s73
	s_cmp_ge_i32 s45, s20
	s_cselect_b32 s72, s20, 0
	s_cselect_b32 s73, 1, 0
	s_sub_i32 s45, s45, s72
	s_add_i32 s44, s44, s73
	v_cvt_f32_u32_e32 v170, s43
	v_cvt_f32_u32_e32 v171, s20
	v_rcp_f32_e32 v171, v171
	s_nop 1
	v_mul_f32_e32 v170, v170, v171
	v_cvt_u32_f32_e32 v170, v170
	s_nop 1
	v_readfirstlane_b32 s46, v170
	s_mul_i32 s72, s46, s20
	s_sub_i32 s47, s43, s72
	s_cmp_lt_i32 s47, 0
	s_cselect_b32 s72, s20, 0
	s_cselect_b32 s73, 1, 0
	s_add_i32 s47, s47, s72
	s_sub_i32 s46, s46, s73
	s_cmp_ge_i32 s47, s20
	s_cselect_b32 s72, s20, 0
	s_cselect_b32 s73, 1, 0
	s_sub_i32 s47, s47, s72
	s_add_i32 s46, s46, s73
	s_cmp_ge_i32 s47, s20
	s_cselect_b32 s72, s20, 0
	s_cselect_b32 s73, 1, 0
	s_sub_i32 s47, s47, s72
	s_add_i32 s46, s46, s73
	v_mul_lo_u32 v168, v161, s10
	v_add_u32_e32 v168, v168, v162
	v_lshlrev_b32_e32 v168, 2, v168
	v_mul_lo_u32 v169, v165, s11
	v_lshl_add_u32 v169, v164, 3, v169
	v_lshlrev_b32_e32 v169, 1, v169
	s_lshl_b32 s48, s10, 4
	s_lshl_b32 s49, s11, 4
	s_mov_b32 s51, s43
	s_mov_b32 s52, s46
	s_mov_b32 s53, s47
	s_mov_b32 s50, s43
	s_mul_i32 s4, s46, s10
	s_add_i32 s4, s4, s47
	s_lshl_b32 s4, s4, 8
	s_add_u32 s56, s24, s4
	s_addc_u32 s57, s25, 0
	global_load_dwordx4 v[0:3], v168, s[56:57] nt
	s_add_u32 s56, s56, s48
	s_addc_u32 s57, s57, 0
	global_load_dwordx4 v[4:7], v168, s[56:57] nt
	s_add_u32 s56, s56, s48
	s_addc_u32 s57, s57, 0
	global_load_dwordx4 v[8:11], v168, s[56:57] nt
	s_add_u32 s56, s56, s48
	s_addc_u32 s57, s57, 0
	global_load_dwordx4 v[12:15], v168, s[56:57] nt
	s_add_u32 s56, s56, s48
	s_addc_u32 s57, s57, 0
	global_load_dwordx4 v[16:19], v168, s[56:57] nt
	s_add_u32 s56, s56, s48
	s_addc_u32 s57, s57, 0
	global_load_dwordx4 v[20:23], v168, s[56:57] nt
	s_add_u32 s56, s56, s48
	s_addc_u32 s57, s57, 0
	global_load_dwordx4 v[24:27], v168, s[56:57] nt
	s_add_u32 s56, s56, s48
	s_addc_u32 s57, s57, 0
	global_load_dwordx4 v[28:31], v168, s[56:57] nt
	s_add_u32 s56, s56, s48
	s_addc_u32 s57, s57, 0
	global_load_dwordx4 v[32:35], v168, s[56:57] nt
	s_add_u32 s56, s56, s48
	s_addc_u32 s57, s57, 0
	global_load_dwordx4 v[36:39], v168, s[56:57] nt
	s_add_u32 s56, s56, s48
	s_addc_u32 s57, s57, 0
	global_load_dwordx4 v[40:43], v168, s[56:57] nt
	s_add_u32 s56, s56, s48
	s_addc_u32 s57, s57, 0
	global_load_dwordx4 v[44:47], v168, s[56:57] nt
	s_add_u32 s56, s56, s48
	s_addc_u32 s57, s57, 0
	global_load_dwordx4 v[48:51], v168, s[56:57] nt
	s_add_u32 s56, s56, s48
	s_addc_u32 s57, s57, 0
	global_load_dwordx4 v[52:55], v168, s[56:57] nt
	s_add_u32 s56, s56, s48
	s_addc_u32 s57, s57, 0
	global_load_dwordx4 v[56:59], v168, s[56:57] nt
	s_add_u32 s56, s56, s48
	s_addc_u32 s57, s57, 0
	global_load_dwordx4 v[60:63], v168, s[56:57] nt
	s_add_i32 s50, s50, s63
	s_add_i32 s47, s47, s45
	s_add_i32 s46, s46, s44
	s_cmp_ge_u32 s47, s20
	s_cselect_b32 s4, s20, 0
	s_cselect_b32 s5, 1, 0
	s_sub_i32 s47, s47, s4
	s_add_i32 s46, s46, s5
	s_cmp_lt_i32 s50, s42
	s_cbranch_scc0 cvp_pre
	s_mul_i32 s4, s46, s10
	s_add_i32 s4, s4, s47
	s_lshl_b32 s4, s4, 8
	s_add_u32 s56, s24, s4
	s_addc_u32 s57, s25, 0
	global_load_dwordx4 v[64:67], v168, s[56:57] nt
	s_add_u32 s56, s56, s48
	s_addc_u32 s57, s57, 0
	global_load_dwordx4 v[68:71], v168, s[56:57] nt
	s_add_u32 s56, s56, s48
	s_addc_u32 s57, s57, 0
	global_load_dwordx4 v[72:75], v168, s[56:57] nt
	s_add_u32 s56, s56, s48
	s_addc_u32 s57, s57, 0
	global_load_dwordx4 v[76:79], v168, s[56:57] nt
	s_add_u32 s56, s56, s48
	s_addc_u32 s57, s57, 0
	global_load_dwordx4 v[80:83], v168, s[56:57] nt
	s_add_u32 s56, s56, s48
	s_addc_u32 s57, s57, 0
	global_load_dwordx4 v[84:87], v168, s[56:57] nt
	s_add_u32 s56, s56, s48
	s_addc_u32 s57, s57, 0
	global_load_dwordx4 v[88:91], v168, s[56:57] nt
	s_add_u32 s56, s56, s48
	s_addc_u32 s57, s57, 0
	global_load_dwordx4 v[92:95], v168, s[56:57] nt
	s_add_u32 s56, s56, s48
	s_addc_u32 s57, s57, 0
	global_load_dwordx4 v[96:99], v168, s[56:57] nt
	s_add_u32 s56, s56, s48
	s_addc_u32 s57, s57, 0
	global_load_dwordx4 v[100:103], v168, s[56:57] nt
	s_add_u32 s56, s56, s48
	s_addc_u32 s57, s57, 0
	global_load_dwordx4 v[104:107], v168, s[56:57] nt
	s_add_u32 s56, s56, s48
	s_addc_u32 s57, s57, 0
	global_load_dwordx4 v[108:111], v168, s[56:57] nt
	s_add_u32 s56, s56, s48
	s_addc_u32 s57, s57, 0
	global_load_dwordx4 v[112:115], v168, s[56:57] nt
	s_add_u32 s56, s56, s48
	s_addc_u32 s57, s57, 0
	global_load_dwordx4 v[116:119], v168, s[56:57] nt
	s_add_u32 s56, s56, s48
	s_addc_u32 s57, s57, 0
	global_load_dwordx4 v[120:123], v168, s[56:57] nt
	s_add_u32 s56, s56, s48
	s_addc_u32 s57, s57, 0
	global_load_dwordx4 v[124:127], v168, s[56:57] nt
	s_add_i32 s50, s50, s63
	s_add_i32 s47, s47, s45
	s_add_i32 s46, s46, s44
	s_cmp_ge_u32 s47, s20
	s_cselect_b32 s4, s20, 0
	s_cselect_b32 s5, 1, 0
	s_sub_i32 s47, s47, s4
	s_add_i32 s46, s46, s5

; #define LAS __attribute__((address_space(3)))
; #define LDS_WAIT() asm volatile("s_waitcnt lgkmcnt(0)" ::: "memory")
; __device__ __forceinline__ void tr_to_lds(const f32x4 (&v)[16], LAS float* scr, int lane) {
;     const int r4 = lane >> 4, c4 = (lane & 15) * 4;
; #pragma unroll
;     for (int i = 0; i < 16; ++i) { LAS float* s = scr + (4 * i + r4) * 65 + c4; s[0] = v[i].x; s[1] = v[i].y; s[2] = v[i].z; s[3] = v[i].w; }
;     LDS_WAIT(); asm volatile("" ::: "memory");
; __device__ __forceinline__ void convert_segments(const Args& args, unsigned char* ws, LAS unsigned char* lds, int seg_lo, int seg_hi, int part_lo, int part_hi, int nparts, int wid, int nw, int wave, int lane) {
;     ...
;         for (; it < it_hi; it += nw) {
;             const int kb = it / nblk, nb = it - kb * nblk;
;             const int drow = sg.ilv ? (256 * (nb >> 1) + 64 * (nb & 1) + sg.drow) : (sg.drow + 64 * nb);
;             tr_to_lds(v, scr, lane);
;             const int itn = it + nw;
;             if (itn < it_hi) { const int kbn = itn / nblk, nbn = itn - kbn * nblk; tr_load(W + (size_t)(64 * kbn) * sg.N + sg.scol + 64 * nbn, sg.N, v, lane); }
cvp_goA:
	ds_write_b32 v163, v0 offset:0
	ds_write_b32 v163, v1 offset:4
	ds_write_b32 v163, v2 offset:8
	ds_write_b32 v163, v3 offset:12
	ds_write_b32 v163, v4 offset:1040
	ds_write_b32 v163, v5 offset:1044
	ds_write_b32 v163, v6 offset:1048
	ds_write_b32 v163, v7 offset:1052
	ds_write_b32 v163, v8 offset:2080
	ds_write_b32 v163, v9 offset:2084
	ds_write_b32 v163, v10 offset:2088
	ds_write_b32 v163, v11 offset:2092
	ds_write_b32 v163, v12 offset:3120
	ds_write_b32 v163, v13 offset:3124
	ds_write_b32 v163, v14 offset:3128
	ds_write_b32 v163, v15 offset:3132
	ds_write_b32 v163, v16 offset:4160
	ds_write_b32 v163, v17 offset:4164
	ds_write_b32 v163, v18 offset:4168
	ds_write_b32 v163, v19 offset:4172
	ds_write_b32 v163, v20 offset:5200
	ds_write_b32 v163, v21 offset:5204
	ds_write_b32 v163, v22 offset:5208
	ds_write_b32 v163, v23 offset:5212
	ds_write_b32 v163, v24 offset:6240
	ds_write_b32 v163, v25 offset:6244
	ds_write_b32 v163, v26 offset:6248
	ds_write_b32 v163, v27 offset:6252
	ds_write_b32 v163, v28 offset:7280
	ds_write_b32 v163, v29 offset:7284
	ds_write_b32 v163, v30 offset:7288
	ds_write_b32 v163, v31 offset:7292
	ds_write_b32 v163, v32 offset:8320
	ds_write_b32 v163, v33 offset:8324
	ds_write_b32 v163, v34 offset:8328
	ds_write_b32 v163, v35 offset:8332
	ds_write_b32 v163, v36 offset:9360
	ds_write_b32 v163, v37 offset:9364
	ds_write_b32 v163, v38 offset:9368
	ds_write_b32 v163, v39 offset:9372
	ds_write_b32 v163, v40 offset:10400
	ds_write_b32 v163, v41 offset:10404
	ds_write_b32 v163, v42 offset:10408
	ds_write_b32 v163, v43 offset:10412
	ds_write_b32 v163, v44 offset:11440
	ds_write_b32 v163, v45 offset:11444
	ds_write_b32 v163, v46 offset:11448
	ds_write_b32 v163, v47 offset:11452
	ds_write_b32 v163, v48 offset:12480
	ds_write_b32 v163, v49 offset:12484
	ds_write_b32 v163, v50 offset:12488
	ds_write_b32 v163, v51 offset:12492
	ds_write_b32 v163, v52 offset:13520
	ds_write_b32 v163, v53 offset:13524
	ds_write_b32 v163, v54 offset:13528
	ds_write_b32 v163, v55 offset:13532
	ds_write_b32 v163, v56 offset:14560
	ds_write_b32 v163, v57 offset:14564
	ds_write_b32 v163, v58 offset:14568
	ds_write_b32 v163, v59 offset:14572
	ds_write_b32 v163, v60 offset:15600
	ds_write_b32 v163, v61 offset:15604
	ds_write_b32 v163, v62 offset:15608
	ds_write_b32 v163, v63 offset:15612
	s_waitcnt lgkmcnt(0)
	s_cmp_lt_i32 s50, s42
	s_cbranch_scc0 cvp_nlA
	s_mul_i32 s4, s46, s10
	s_add_i32 s4, s4, s47
	s_lshl_b32 s4, s4, 8
	s_add_u32 s56, s24, s4
	s_addc_u32 s57, s25, 0
	global_load_dwordx4 v[0:3], v168, s[56:57] nt
	s_add_u32 s56, s56, s48
	s_addc_u32 s57, s57, 0
	global_load_dwordx4 v[4:7], v168, s[56:57] nt
	s_add_u32 s56, s56, s48
	s_addc_u32 s57, s57, 0
	global_load_dwordx4 v[8:11], v168, s[56:57] nt
	s_add_u32 s56, s56, s48
	s_addc_u32 s57, s57, 0
	global_load_dwordx4 v[12:15], v168, s[56:57] nt
	s_add_u32 s56, s56, s48
	s_addc_u32 s57, s57, 0
	global_load_dwordx4 v[16:19], v168, s[56:57] nt
	s_add_u32 s56, s56, s48
	s_addc_u32 s57, s57, 0
	global_load_dwordx4 v[20:23], v168, s[56:57] nt
	s_add_u32 s56, s56, s48
	s_addc_u32 s57, s57, 0
	global_load_dwordx4 v[24:27], v168, s[56:57] nt
	s_add_u32 s56, s56, s48
	s_addc_u32 s57, s57, 0
	global_load_dwordx4 v[28:31], v168, s[56:57] nt
	s_add_u32 s56, s56, s48
	s_addc_u32 s57, s57, 0
	global_load_dwordx4 v[32:35], v168, s[56:57] nt
	s_add_u32 s56, s56, s48
	s_addc_u32 s57, s57, 0
	global_load_dwordx4 v[36:39], v168, s[56:57] nt
	s_add_u32 s56, s56, s48
	s_addc_u32 s57, s57, 0
	global_load_dwordx4 v[40:43], v168, s[56:57] nt
	s_add_u32 s56, s56, s48
	s_addc_u32 s57, s57, 0
	global_load_dwordx4 v[44:47], v168, s[56:57] nt
	s_add_u32 s56, s56, s48
	s_addc_u32 s57, s57, 0
	global_load_dwordx4 v[48:51], v168, s[56:57] nt
	s_add_u32 s56, s56, s48
	s_addc_u32 s57, s57, 0
	global_load_dwordx4 v[52:55], v168, s[56:57] nt
	s_add_u32 s56, s56, s48
	s_addc_u32 s57, s57, 0
	global_load_dwordx4 v[56:59], v168, s[56:57] nt
	s_add_u32 s56, s56, s48
	s_addc_u32 s57, s57, 0
	global_load_dwordx4 v[60:63], v168, s[56:57] nt
	s_add_i32 s50, s50, s63
	s_add_i32 s47, s47, s45
	s_add_i32 s46, s46, s44
	s_cmp_ge_u32 s47, s20
	s_cselect_b32 s4, s20, 0
	s_cselect_b32 s5, 1, 0
	s_sub_i32 s47, s47, s4
	s_add_i32 s46, s46, s5

; #define LAS __attribute__((address_space(3)))
; #define LDS_WAIT() asm volatile("s_waitcnt lgkmcnt(0)" ::: "memory")
; __device__ __forceinline__ void tr_to_lds(const f32x4 (&v)[16], LAS float* scr, int lane) {
;     const int r4 = lane >> 4, c4 = (lane & 15) * 4;
; #pragma unroll
;     for (int i = 0; i < 16; ++i) { LAS float* s = scr + (4 * i + r4) * 65 + c4; s[0] = v[i].x; s[1] = v[i].y; s[2] = v[i].z; s[3] = v[i].w; }
;     LDS_WAIT(); asm volatile("" ::: "memory");
; __device__ __forceinline__ void convert_segments(const Args& args, unsigned char* ws, LAS unsigned char* lds, int seg_lo, int seg_hi, int part_lo, int part_hi, int nparts, int wid, int nw, int wave, int lane) {
;     ...
;         for (; it < it_hi; it += nw) {
;             const int kb = it / nblk, nb = it - kb * nblk;
;             const int drow = sg.ilv ? (256 * (nb >> 1) + 64 * (nb & 1) + sg.drow) : (sg.drow + 64 * nb);
;             tr_to_lds(v, scr, lane);
;             const int itn = it + nw;
;             if (itn < it_hi) { const int kbn = itn / nblk, nbn = itn - kbn * nblk; tr_load(W + (size_t)(64 * kbn) * sg.N + sg.scol + 64 * nbn, sg.N, v, lane); }
cvp_goB:
	ds_write_b32 v163, v64 offset:0
	ds_write_b32 v163, v65 offset:4
	ds_write_b32 v163, v66 offset:8
	ds_write_b32 v163, v67 offset:12
	ds_write_b32 v163, v68 offset:1040
	ds_write_b32 v163, v69 offset:1044
	ds_write_b32 v163, v70 offset:1048
	ds_write_b32 v163, v71 offset:1052
	ds_write_b32 v163, v72 offset:2080
	ds_write_b32 v163, v73 offset:2084
	ds_write_b32 v163, v74 offset:2088
	ds_write_b32 v163, v75 offset:2092
	ds_write_b32 v163, v76 offset:3120
	ds_write_b32 v163, v77 offset:3124
	ds_write_b32 v163, v78 offset:3128
	ds_write_b32 v163, v79 offset:3132
	ds_write_b32 v163, v80 offset:4160
	ds_write_b32 v163, v81 offset:4164
	ds_write_b32 v163, v82 offset:4168
	ds_write_b32 v163, v83 offset:4172
	ds_write_b32 v163, v84 offset:5200
	ds_write_b32 v163, v85 offset:5204
	ds_write_b32 v163, v86 offset:5208
	ds_write_b32 v163, v87 offset:5212
	ds_write_b32 v163, v88 offset:6240
	ds_write_b32 v163, v89 offset:6244
	ds_write_b32 v163, v90 offset:6248
	ds_write_b32 v163, v91 offset:6252
	ds_write_b32 v163, v92 offset:7280
	ds_write_b32 v163, v93 offset:7284
	ds_write_b32 v163, v94 offset:7288
	ds_write_b32 v163, v95 offset:7292
	ds_write_b32 v163, v96 offset:8320
	ds_write_b32 v163, v97 offset:8324
	ds_write_b32 v163, v98 offset:8328
	ds_write_b32 v163, v99 offset:8332
	ds_write_b32 v163, v100 offset:9360
	ds_write_b32 v163, v101 offset:9364
	ds_write_b32 v163, v102 offset:9368
	ds_write_b32 v163, v103 offset:9372
	ds_write_b32 v163, v104 offset:10400
	ds_write_b32 v163, v105 offset:10404
	ds_write_b32 v163, v106 offset:10408
	ds_write_b32 v163, v107 offset:10412
	ds_write_b32 v163, v108 offset:11440
	ds_write_b32 v163, v109 offset:11444
	ds_write_b32 v163, v110 offset:11448
	ds_write_b32 v163, v111 offset:11452
	ds_write_b32 v163, v112 offset:12480
	ds_write_b32 v163, v113 offset:12484
	ds_write_b32 v163, v114 offset:12488
	ds_write_b32 v163, v115 offset:12492
	ds_write_b32 v163, v116 offset:13520
	ds_write_b32 v163, v117 offset:13524
	ds_write_b32 v163, v118 offset:13528
	ds_write_b32 v163, v119 offset:13532
	ds_write_b32 v163, v120 offset:14560
	ds_write_b32 v163, v121 offset:14564
	ds_write_b32 v163, v122 offset:14568
	ds_write_b32 v163, v123 offset:14572
	ds_write_b32 v163, v124 offset:15600
	ds_write_b32 v163, v125 offset:15604
	ds_write_b32 v163, v126 offset:15608
	ds_write_b32 v163, v127 offset:15612
	s_waitcnt lgkmcnt(0)
	s_cmp_lt_i32 s50, s42
	s_cbranch_scc0 cvp_nlB
	s_mul_i32 s4, s46, s10
	s_add_i32 s4, s4, s47
	s_lshl_b32 s4, s4, 8
	s_add_u32 s56, s24, s4
	s_addc_u32 s57, s25, 0
	global_load_dwordx4 v[64:67], v168, s[56:57] nt
	s_add_u32 s56, s56, s48
	s_addc_u32 s57, s57, 0
	global_load_dwordx4 v[68:71], v168, s[56:57] nt
	s_add_u32 s56, s56, s48
	s_addc_u32 s57, s57, 0
	global_load_dwordx4 v[72:75], v168, s[56:57] nt
	s_add_u32 s56, s56, s48
	s_addc_u32 s57, s57, 0
	global_load_dwordx4 v[76:79], v168, s[56:57] nt
	s_add_u32 s56, s56, s48
	s_addc_u32 s57, s57, 0
	global_load_dwordx4 v[80:83], v168, s[56:57] nt
	s_add_u32 s56, s56, s48
	s_addc_u32 s57, s57, 0
	global_load_dwordx4 v[84:87], v168, s[56:57] nt
	s_add_u32 s56, s56, s48
	s_addc_u32 s57, s57, 0
	global_load_dwordx4 v[88:91], v168, s[56:57] nt
	s_add_u32 s56, s56, s48
	s_addc_u32 s57, s57, 0
	global_load_dwordx4 v[92:95], v168, s[56:57] nt
	s_add_u32 s56, s56, s48
	s_addc_u32 s57, s57, 0
	global_load_dwordx4 v[96:99], v168, s[56:57] nt
	s_add_u32 s56, s56, s48
	s_addc_u32 s57, s57, 0
	global_load_dwordx4 v[100:103], v168, s[56:57] nt
	s_add_u32 s56, s56, s48
	s_addc_u32 s57, s57, 0
	global_load_dwordx4 v[104:107], v168, s[56:57] nt
	s_add_u32 s56, s56, s48
	s_addc_u32 s57, s57, 0
	global_load_dwordx4 v[108:111], v168, s[56:57] nt
	s_add_u32 s56, s56, s48
	s_addc_u32 s57, s57, 0
	global_load_dwordx4 v[112:115], v168, s[56:57] nt
	s_add_u32 s56, s56, s48
	s_addc_u32 s57, s57, 0
	global_load_dwordx4 v[116:119], v168, s[56:57] nt
	s_add_u32 s56, s56, s48
	s_addc_u32 s57, s57, 0
	global_load_dwordx4 v[120:123], v168, s[56:57] nt
	s_add_u32 s56, s56, s48
	s_addc_u32 s57, s57, 0
	global_load_dwordx4 v[124:127], v168, s[56:57] nt
	s_add_i32 s50, s50, s63
	s_add_i32 s47, s47, s45
	s_add_i32 s46, s46, s44
	s_cmp_ge_u32 s47, s20
	s_cselect_b32 s4, s20, 0
	s_cselect_b32 s5, 1, 0
	s_sub_i32 s47, s47, s4
	s_add_i32 s46, s46, s5
